# PEER coefficient loop: the two tokens of a trip processed in lock-step (reads, table loads and the six-step cross-lane max issued pairwise) instead of back to back
# baseline (speedup 1.0000x reference)
.LBB0_1389:
	s_add_i32 s48, s44, s33
	s_ashr_i32 s49, s48, 31
	s_lshl_b64 s[50:51], s[48:49], 2
	v_add_u32_e32 v5, 0, v2
	s_add_u32 s50, s57, s50
	v_add_u32_e32 v3, 0, v1
	v_add_u32_e32 v4, 0x10000, v5
	v_add_u32_e32 v6, 0x10100, v5
	s_addc_u32 s51, s58, s51
	s_add_i32 s48, s48, 1
	s_ashr_i32 s49, s48, 31
	s_lshl_b64 s[48:49], s[48:49], 2
	s_add_u32 s48, s57, s48
	s_addc_u32 s49, s58, s49
	v_add_u32_e32 v24, 0x10200, v5
	v_add_u32_e32 v26, 0x10300, v5
	ds_read_u16 v7, v3
	ds_read_u16 v8, v3 offset:128
	ds_read_b32 v4, v4
	ds_read_b32 v6, v6
	ds_read_u16 v9, v3 offset:32896
	global_load_dword v10, v149, s[50:51]
	ds_read_u16 v13, v3 offset:32768
	ds_read_u16 v27, v3 offset:256
	ds_read_u16 v28, v3 offset:384
	ds_read_b32 v24, v24
	ds_read_b32 v26, v26
	ds_read_u16 v29, v3 offset:33152
	global_load_dword v30, v149, s[48:49]
	ds_read_u16 v33, v3 offset:33024
	s_waitcnt lgkmcnt(0)
	v_lshlrev_b32_e32 v7, 2, v7
	v_lshlrev_b32_e32 v8, 2, v8
	global_load_dword v11, v7, s[34:35]
	global_load_dword v12, v8, s[34:35]
	s_nop 0
	global_load_dword v7, v7, s[38:39]
	s_nop 0
	global_load_dword v8, v8, s[38:39]
	v_lshlrev_b32_e32 v27, 2, v27
	v_lshlrev_b32_e32 v28, 2, v28
	global_load_dword v31, v27, s[34:35]
	global_load_dword v32, v28, s[34:35]
	s_nop 0
	global_load_dword v27, v27, s[38:39]
	s_nop 0
	global_load_dword v28, v28, s[38:39]
	v_cvt_f32_i32_e32 v4, v4
	v_cvt_f32_i32_e32 v6, v6
	v_cvt_f32_f16_e32 v9, v9
	v_cvt_f32_i32_e32 v24, v24
	v_cvt_f32_i32_e32 v26, v26
	v_cvt_f32_f16_e32 v29, v29
	s_waitcnt vmcnt(0)
	v_mul_f32_e32 v4, v10, v4
	v_mul_f32_e32 v6, v10, v6
	v_mul_f32_e32 v4, v4, v11
	v_mul_f32_e32 v6, v6, v12
	v_mul_f32_e32 v10, 0x3d372713, v4
	v_mul_f32_e32 v11, 0x3d372713, v6
	v_mul_f32_e32 v10, v4, v10
	v_mul_f32_e32 v11, v6, v11
	v_fma_f32 v10, v4, v10, v4
	v_fma_f32 v11, v6, v11, v6
	v_mul_f32_e32 v10, 0x3f4c422a, v10
	v_mul_f32_e32 v11, 0x3f4c422a, v11
	v_add_f32_e32 v10, v10, v10
	v_add_f32_e32 v11, v11, v11
	v_mul_f32_e32 v10, 0x3fb8aa3b, v10
	v_mul_f32_e32 v11, 0x3fb8aa3b, v11
	v_exp_f32_e32 v10, v10
	v_exp_f32_e32 v11, v11
	v_cvt_f32_f16_e32 v12, v13
	v_mul_f32_e32 v4, 0.5, v4
	v_add_f32_e32 v10, 1.0, v10
	v_add_f32_e32 v11, 1.0, v11
	v_rcp_f32_e32 v10, v10
	v_rcp_f32_e32 v11, v11
	v_mul_f32_e32 v6, 0.5, v6
	v_fma_f32 v10, v10, -2.0, 1.0
	v_fma_f32 v11, v11, -2.0, 1.0
	v_add_f32_e32 v10, 1.0, v10
	v_add_f32_e32 v11, 1.0, v11
	v_mul_f32_e32 v4, v4, v10
	v_mul_f32_e32 v6, v6, v11
	v_mul_f32_e32 v4, v4, v12
	v_mul_f32_e32 v6, v6, v9
	v_mul_f32_e32 v7, v7, v4
	v_mul_f32_e32 v8, v8, v6
	v_max_f32_e64 v4, |v7|, |v8|
	v_mul_f32_e32 v24, v30, v24
	v_mul_f32_e32 v26, v30, v26
	v_mul_f32_e32 v24, v24, v31
	v_mul_f32_e32 v26, v26, v32
	v_mul_f32_e32 v30, 0x3d372713, v24
	v_mul_f32_e32 v31, 0x3d372713, v26
	v_mul_f32_e32 v30, v24, v30
	v_mul_f32_e32 v31, v26, v31
	v_fma_f32 v30, v24, v30, v24
	v_fma_f32 v31, v26, v31, v26
	v_mul_f32_e32 v30, 0x3f4c422a, v30
	v_mul_f32_e32 v31, 0x3f4c422a, v31
	v_add_f32_e32 v30, v30, v30
	v_add_f32_e32 v31, v31, v31
	v_mul_f32_e32 v30, 0x3fb8aa3b, v30
	v_mul_f32_e32 v31, 0x3fb8aa3b, v31
	v_exp_f32_e32 v30, v30
	v_exp_f32_e32 v31, v31
	v_cvt_f32_f16_e32 v32, v33
	v_mul_f32_e32 v24, 0.5, v24
	v_add_f32_e32 v30, 1.0, v30
	v_add_f32_e32 v31, 1.0, v31
	v_rcp_f32_e32 v30, v30
	v_rcp_f32_e32 v31, v31
	v_mul_f32_e32 v26, 0.5, v26
	v_fma_f32 v30, v30, -2.0, 1.0
	v_fma_f32 v31, v31, -2.0, 1.0
	v_add_f32_e32 v30, 1.0, v30
	v_add_f32_e32 v31, 1.0, v31
	v_mul_f32_e32 v24, v24, v30
	v_mul_f32_e32 v26, v26, v31
	v_mul_f32_e32 v24, v24, v32
	v_mul_f32_e32 v26, v26, v29
	v_mul_f32_e32 v27, v27, v24
	v_mul_f32_e32 v28, v28, v26
	v_max_f32_e64 v24, |v27|, |v28|
	ds_bpermute_b32 v6, v189, v4
	ds_bpermute_b32 v26, v189, v24
	s_waitcnt lgkmcnt(0)
	v_max_f32_e32 v6, v6, v6
	v_max_f32_e32 v4, v4, v6
	v_max_f32_e32 v26, v26, v26
	v_max_f32_e32 v24, v24, v26
	ds_bpermute_b32 v6, v190, v4
	ds_bpermute_b32 v26, v190, v24
	s_waitcnt lgkmcnt(0)
	v_max_f32_e32 v6, v6, v6
	v_max_f32_e32 v4, v4, v6
	v_max_f32_e32 v26, v26, v26
	v_max_f32_e32 v24, v24, v26
	ds_bpermute_b32 v6, v191, v4
	ds_bpermute_b32 v26, v191, v24
	s_waitcnt lgkmcnt(0)
	v_max_f32_e32 v6, v6, v6
	v_max_f32_e32 v4, v4, v6
	v_max_f32_e32 v26, v26, v26
	v_max_f32_e32 v24, v24, v26
	ds_bpermute_b32 v6, v192, v4
	ds_bpermute_b32 v26, v192, v24
	s_waitcnt lgkmcnt(0)
	v_max_f32_e32 v6, v6, v6
	v_max_f32_e32 v4, v4, v6
	v_max_f32_e32 v26, v26, v26
	v_max_f32_e32 v24, v24, v26
	ds_bpermute_b32 v6, v193, v4
	ds_bpermute_b32 v26, v193, v24
	s_waitcnt lgkmcnt(0)
	v_max_f32_e32 v6, v6, v6
	v_max_f32_e32 v4, v4, v6
	v_max_f32_e32 v26, v26, v26
	v_max_f32_e32 v24, v24, v26
	ds_bpermute_b32 v6, v194, v4
	ds_bpermute_b32 v26, v194, v24
	s_waitcnt lgkmcnt(0)
	v_max3_f32 v6, v4, v6, s69
	v_max3_f32 v26, v24, v26, s69
	v_div_scale_f32 v9, s[50:51], v6, v6, s70
	v_rcp_f32_e32 v10, v9
	v_div_scale_f32 v11, vcc, s70, v6, s70
	v_add_u32_e32 v4, 0, v0
	v_fma_f32 v12, -v9, v10, 1.0
	v_fmac_f32_e32 v10, v12, v10
	v_mul_f32_e32 v12, v11, v10
	v_fma_f32 v13, -v9, v12, v11
	v_fmac_f32_e32 v12, v13, v10
	v_fma_f32 v9, -v9, v12, v11
	v_div_fmas_f32 v9, v9, v10, v12
	v_div_fixup_f32 v9, v9, v6, s70
	v_mul_f32_e32 v7, v7, v9
	v_mul_f32_e32 v8, v8, v9
	v_rndne_f32_e32 v7, v7
	v_rndne_f32_e32 v8, v8
	v_cvt_i32_f32_e32 v7, v7
	v_cvt_i32_f32_e32 v8, v8
	v_add_u32_e32 v9, 0x10000, v4
	v_add_u32_e32 v10, 0x10040, v4
	ds_write_b8 v9, v7
	ds_write_b8 v10, v8
	s_and_saveexec_b64 s[50:51], s[4:5]
	s_add_i32 s45, s40, 0
	s_add_i32 s45, s45, 0x20000
	v_mul_f32_e32 v6, 0x3c010204, v6
	v_mov_b32_e32 v7, s45
	ds_write_b32 v7, v6
	s_or_b64 exec, exec, s[50:51]
	v_div_scale_f32 v29, s[48:49], v26, v26, s70
	v_rcp_f32_e32 v30, v29
	v_div_scale_f32 v31, vcc, s70, v26, s70
	v_add_u32_e32 v24, 0, v0
	v_fma_f32 v32, -v29, v30, 1.0
	v_fmac_f32_e32 v30, v32, v30
	v_mul_f32_e32 v32, v31, v30
	v_fma_f32 v33, -v29, v32, v31
	v_fmac_f32_e32 v32, v33, v30
	v_fma_f32 v29, -v29, v32, v31
	v_div_fmas_f32 v29, v29, v30, v32
	v_div_fixup_f32 v29, v29, v26, s70
	v_mul_f32_e32 v27, v27, v29
	v_mul_f32_e32 v28, v28, v29
	v_rndne_f32_e32 v27, v27
	v_rndne_f32_e32 v28, v28
	v_cvt_i32_f32_e32 v27, v27
	v_cvt_i32_f32_e32 v28, v28
	v_add_u32_e32 v29, 0x10080, v24
	v_add_u32_e32 v30, 0x100c0, v24
	ds_write_b8 v29, v27
	ds_write_b8 v30, v28
	s_and_saveexec_b64 s[48:49], s[4:5]
	s_add_i32 s45, s40, 0
	s_add_i32 s45, s45, 0x20004
	v_mul_f32_e32 v26, 0x3c010204, v26
	v_mov_b32_e32 v27, s45
	ds_write_b32 v27, v26
	s_branch .LBB0_1388
